# SwiGLU epilogue: cache per-row rms statistics in VGPRs across tiles with unchanged pm (no ssq reload, no vmcnt wait)
# speedup vs baseline: 1.0266x; 1.0080x over previous
.LBB0_503:
	s_mov_b32 s98, -1
	s_waitcnt vmcnt(8)
	v_mov_b32_e32 v12, v150
	s_barrier
	s_xor_b64 s[10:11], s[10:11], -1
	v_bfe_i32 v1, v12, 27, 1
	v_lshlrev_b32_e32 v5, 4, v12
	v_lshrrev_b32_e32 v1, 22, v1
	v_add_u32_e32 v1, v5, v1
	v_and_b32_e32 v1, 0xfffffc00, v1
	v_sub_u32_e32 v1, v5, v1
	v_ashrrev_i32_e32 v0, 31, v12
	v_lshrrev_b32_e32 v2, 4, v1
	v_lshrrev_b32_e32 v0, 26, v0
	v_bitop3_b32 v1, v2, v1, 32 bitop3:0x6c
	v_add_u32_e32 v0, v12, v0
	v_ashrrev_i32_e32 v3, 31, v1
	v_ashrrev_i32_e32 v0, 6, v0
	v_lshrrev_b32_e32 v3, 26, v3
	v_lshlrev_b32_e32 v2, 3, v0
	v_add_u32_e32 v3, v1, v3
	v_and_b32_e32 v2, -16, v2
	v_ashrrev_i32_e32 v3, 6, v3
	v_add_u32_e32 v2, v3, v2
	v_readfirstlane_b32 s87, v12
	s_and_b64 vcc, exec, s[10:11]
	v_mov_b32_e32 v4, v2
	s_cbranch_vccz .LBB0_505
	v_lshlrev_b32_e32 v4, 1, v2
	v_lshrrev_b32_e32 v6, 2, v2
	v_and_b32_e32 v7, 3, v3
	s_movk_i32 s0, 0xffe0
	v_and_b32_e32 v4, 24, v4
	v_and_b32_e32 v6, 4, v6
	v_and_or_b32 v7, v2, s0, v7
	v_or3_b32 v4, v7, v6, v4

.LBB0_537:
	s_andn2_b64 vcc, exec, s[10:11]
	s_cbranch_vccnz .LBB0_514
	s_mov_b64 s[10:11], -1
	s_cmp_eq_u32 s45, 1
	v_ashrrev_i32_e32 v163, 31, v162
	v_or_b32_e32 v134, 16, v162
	v_or_b32_e32 v130, 32, v162
	v_or_b32_e32 v132, 48, v162
	v_add_u32_e32 v128, 0x80, v162
	s_cbranch_scc1 .LBB0_540
	s_cmp_eq_u32 s98, s20
	s_cbranch_scc1 .Lep0_fast
	s_mov_b32 s98, s20
	v_lshlrev_b64 v[164:165], 6, v[162:163]
	v_lshl_add_u64 v[164:165], v[156:157], 0, v[164:165]
	s_mov_b64 s[10:11], 0x2000
	global_load_dwordx4 v[190:193], v[164:165], off
	global_load_dwordx4 v[194:197], v[164:165], off offset:1024
	global_load_dwordx4 v[198:201], v[164:165], off offset:2048
	global_load_dwordx4 v[202:205], v[164:165], off offset:3072
	v_lshl_add_u64 v[166:167], v[164:165], 0, s[10:11]
	global_load_dwordx4 v[206:209], v[166:167], off
	global_load_dwordx4 v[210:213], v[166:167], off offset:1024
	global_load_dwordx4 v[214:217], v[166:167], off offset:2048
	global_load_dwordx4 v[218:221], v[166:167], off offset:3072
	v_mov_b32_e32 v173, s56
	s_waitcnt vmcnt(0)
	v_add_f32_e32 v190, v190, v191
	v_add_f32_e32 v194, v194, v195
	v_add_f32_e32 v198, v198, v199
	v_add_f32_e32 v202, v202, v203
	v_add_f32_e32 v206, v206, v207
	v_add_f32_e32 v210, v210, v211
	v_add_f32_e32 v214, v214, v215
	v_add_f32_e32 v218, v218, v219
	v_add_f32_e32 v192, v192, v193
	v_add_f32_e32 v196, v196, v197
	v_add_f32_e32 v200, v200, v201
	v_add_f32_e32 v204, v204, v205
	v_add_f32_e32 v208, v208, v209
	v_add_f32_e32 v212, v212, v213
	v_add_f32_e32 v216, v216, v217
	v_add_f32_e32 v220, v220, v221
	v_add_f32_e32 v242, v190, v192
	v_add_f32_e32 v243, v194, v196
	v_add_f32_e32 v244, v198, v200
	v_add_f32_e32 v245, v202, v204
	v_add_f32_e32 v246, v206, v208
	v_add_f32_e32 v247, v210, v212
	v_add_f32_e32 v248, v214, v216
	v_add_f32_e32 v249, v218, v220
	v_mov_b32_e32 v135, v242
	v_mov_b32_e32 v136, v243
	v_mov_b32_e32 v137, v244
	v_mov_b32_e32 v138, v245
	v_mov_b32_e32 v139, v246
	v_mov_b32_e32 v140, v247
	v_mov_b32_e32 v141, v248
	v_mov_b32_e32 v142, v249
	s_nop 1
	v_permlane16_swap_b32_e32 v242, v135
	v_permlane16_swap_b32_e32 v243, v136
	v_permlane16_swap_b32_e32 v244, v137
	v_permlane16_swap_b32_e32 v245, v138
	v_permlane16_swap_b32_e32 v246, v139
	v_permlane16_swap_b32_e32 v247, v140
	v_permlane16_swap_b32_e32 v248, v141
	v_permlane16_swap_b32_e32 v249, v142
	v_add_f32_e32 v242, v242, v135
	v_add_f32_e32 v243, v243, v136
	v_add_f32_e32 v244, v244, v137
	v_add_f32_e32 v245, v245, v138
	v_add_f32_e32 v246, v246, v139
	v_add_f32_e32 v247, v247, v140
	v_add_f32_e32 v248, v248, v141
	v_add_f32_e32 v249, v249, v142
	v_mov_b32_e32 v135, v242
	v_mov_b32_e32 v136, v243
	v_mov_b32_e32 v137, v244
	v_mov_b32_e32 v138, v245
	v_mov_b32_e32 v139, v246
	v_mov_b32_e32 v140, v247
	v_mov_b32_e32 v141, v248
	v_mov_b32_e32 v142, v249
	s_nop 1
	v_permlane32_swap_b32_e32 v242, v135
	v_permlane32_swap_b32_e32 v243, v136
	v_permlane32_swap_b32_e32 v244, v137
	v_permlane32_swap_b32_e32 v245, v138
	v_permlane32_swap_b32_e32 v246, v139
	v_permlane32_swap_b32_e32 v247, v140
	v_permlane32_swap_b32_e32 v248, v141
	v_permlane32_swap_b32_e32 v249, v142
	v_add_f32_e32 v242, v242, v135
	v_add_f32_e32 v243, v243, v136
	v_add_f32_e32 v244, v244, v137
	v_add_f32_e32 v245, v245, v138
	v_add_f32_e32 v246, v246, v139
	v_add_f32_e32 v247, v247, v140
	v_add_f32_e32 v248, v248, v141
	v_add_f32_e32 v249, v249, v142
	v_fma_f32 v242, v242, s54, v173
	v_fma_f32 v243, v243, s54, v173
	v_fma_f32 v244, v244, s54, v173
	v_fma_f32 v245, v245, s54, v173
	v_fma_f32 v246, v246, s54, v173
	v_fma_f32 v247, v247, s54, v173
	v_fma_f32 v248, v248, s54, v173
	v_fma_f32 v249, v249, s54, v173
	v_rsq_f32_e32 v250, v242
	v_rsq_f32_e32 v251, v243
	v_rsq_f32_e32 v252, v244
	v_rsq_f32_e32 v253, v245
	v_rsq_f32_e32 v168, v246
	v_rsq_f32_e32 v170, v247
	v_rsq_f32_e32 v176, v248
	v_rsq_f32_e32 v178, v249
	s_nop 0
	v_mul_f32_e32 v250, 0xbfb8aa3b, v250
	v_mul_f32_e32 v251, 0xbfb8aa3b, v251
	v_mul_f32_e32 v252, 0xbfb8aa3b, v252
	v_mul_f32_e32 v253, 0xbfb8aa3b, v253
	v_mul_f32_e32 v168, 0xbfb8aa3b, v168
	v_mul_f32_e32 v170, 0xbfb8aa3b, v170
	v_mul_f32_e32 v176, 0xbfb8aa3b, v176
	v_mul_f32_e32 v178, 0xbfb8aa3b, v178
.Lep0_fast:
	v_mad_u64_u32 v[174:175], s[10:11], s28, v162, 0
	v_lshl_or_b32 v164, s25, 7, v186
	v_mov_b32_e32 v165, 0
	s_lshl_b64 s[78:79], s[28:29], 5
	s_lshl_b64 s[84:85], s[28:29], 8
	v_lshl_add_u64 v[174:175], v[174:175], 0, v[164:165]
	v_lshl_add_u64 v[174:175], v[174:175], 1, s[70:71]
	v_lshl_add_u64 v[166:167], v[174:175], 0, s[84:85]
	v_mul_f32_e32 v190, v250, v124
	v_mul_f32_e32 v191, v250, v125
	v_mul_f32_e32 v192, v250, v126
	v_mul_f32_e32 v193, v250, v127
	v_mul_f32_e32 v194, v250, v116
	v_mul_f32_e32 v195, v250, v117
	v_mul_f32_e32 v196, v250, v118
	v_mul_f32_e32 v197, v250, v119
	v_exp_f32_e32 v190, v190
	v_exp_f32_e32 v191, v191
	v_exp_f32_e32 v192, v192
	v_exp_f32_e32 v193, v193
	v_exp_f32_e32 v194, v194
	v_exp_f32_e32 v195, v195
	v_exp_f32_e32 v196, v196
	v_exp_f32_e32 v197, v197
	v_mul_f32_e32 v198, v124, v108
	v_mul_f32_e32 v199, v125, v109
	v_mul_f32_e32 v200, v126, v110
	v_mul_f32_e32 v201, v127, v111
	v_mul_f32_e32 v202, v116, v100
	v_mul_f32_e32 v203, v117, v101
	v_mul_f32_e32 v204, v118, v102
	v_mul_f32_e32 v205, v119, v103
	v_fma_f32 v190, v190, v242, v242
	v_fma_f32 v191, v191, v242, v242
	v_fma_f32 v192, v192, v242, v242
	v_fma_f32 v193, v193, v242, v242
	v_fma_f32 v194, v194, v242, v242
	v_fma_f32 v195, v195, v242, v242
	v_fma_f32 v196, v196, v242, v242
	v_fma_f32 v197, v197, v242, v242
	v_rcp_f32_e32 v190, v190
	v_rcp_f32_e32 v191, v191
	v_rcp_f32_e32 v192, v192
	v_rcp_f32_e32 v193, v193
	v_rcp_f32_e32 v194, v194
	v_rcp_f32_e32 v195, v195
	v_rcp_f32_e32 v196, v196
	v_rcp_f32_e32 v197, v197
	s_nop 0
	v_mul_f32_e32 v198, v198, v190
	v_mul_f32_e32 v199, v199, v191
	v_mul_f32_e32 v200, v200, v192
	v_mul_f32_e32 v201, v201, v193
	v_mul_f32_e32 v202, v202, v194
	v_mul_f32_e32 v203, v203, v195
	v_mul_f32_e32 v204, v204, v196
	v_mul_f32_e32 v205, v205, v197
	v_cvt_pk_bf16_f32 v190, v198, v199
	v_cvt_pk_bf16_f32 v191, v200, v201
	v_cvt_pk_bf16_f32 v192, v202, v203
	v_cvt_pk_bf16_f32 v193, v204, v205
	global_store_dwordx4 v[174:175], v[190:193], off
	v_lshl_add_u64 v[174:175], v[174:175], 0, s[78:79]
	v_mul_f32_e32 v206, v251, v120
	v_mul_f32_e32 v207, v251, v121
	v_mul_f32_e32 v208, v251, v122
	v_mul_f32_e32 v209, v251, v123
	v_mul_f32_e32 v210, v251, v112
	v_mul_f32_e32 v211, v251, v113
	v_mul_f32_e32 v212, v251, v114
	v_mul_f32_e32 v213, v251, v115
	v_exp_f32_e32 v206, v206
	v_exp_f32_e32 v207, v207
	v_exp_f32_e32 v208, v208
	v_exp_f32_e32 v209, v209
	v_exp_f32_e32 v210, v210
	v_exp_f32_e32 v211, v211
	v_exp_f32_e32 v212, v212
	v_exp_f32_e32 v213, v213
	v_mul_f32_e32 v214, v120, v104
	v_mul_f32_e32 v215, v121, v105
	v_mul_f32_e32 v216, v122, v106
	v_mul_f32_e32 v217, v123, v107
	v_mul_f32_e32 v218, v112, v96
	v_mul_f32_e32 v219, v113, v97
	v_mul_f32_e32 v220, v114, v98
	v_mul_f32_e32 v221, v115, v99
	v_fma_f32 v206, v206, v243, v243
	v_fma_f32 v207, v207, v243, v243
	v_fma_f32 v208, v208, v243, v243
	v_fma_f32 v209, v209, v243, v243
	v_fma_f32 v210, v210, v243, v243
	v_fma_f32 v211, v211, v243, v243
	v_fma_f32 v212, v212, v243, v243
	v_fma_f32 v213, v213, v243, v243
	v_rcp_f32_e32 v206, v206
	v_rcp_f32_e32 v207, v207
	v_rcp_f32_e32 v208, v208
	v_rcp_f32_e32 v209, v209
	v_rcp_f32_e32 v210, v210
	v_rcp_f32_e32 v211, v211
	v_rcp_f32_e32 v212, v212
	v_rcp_f32_e32 v213, v213
	s_nop 0
	v_mul_f32_e32 v214, v214, v206
	v_mul_f32_e32 v215, v215, v207
	v_mul_f32_e32 v216, v216, v208
	v_mul_f32_e32 v217, v217, v209
	v_mul_f32_e32 v218, v218, v210
	v_mul_f32_e32 v219, v219, v211
	v_mul_f32_e32 v220, v220, v212
	v_mul_f32_e32 v221, v221, v213
	v_cvt_pk_bf16_f32 v206, v214, v215
	v_cvt_pk_bf16_f32 v207, v216, v217
	v_cvt_pk_bf16_f32 v208, v218, v219
	v_cvt_pk_bf16_f32 v209, v220, v221
	global_store_dwordx4 v[174:175], v[206:209], off
	v_lshl_add_u64 v[174:175], v[174:175], 0, s[78:79]
	v_mul_f32_e32 v190, v252, v92
	v_mul_f32_e32 v191, v252, v93
	v_mul_f32_e32 v192, v252, v94
	v_mul_f32_e32 v193, v252, v95
	v_mul_f32_e32 v194, v252, v84
	v_mul_f32_e32 v195, v252, v85
	v_mul_f32_e32 v196, v252, v86
	v_mul_f32_e32 v197, v252, v87
	v_exp_f32_e32 v190, v190
	v_exp_f32_e32 v191, v191
	v_exp_f32_e32 v192, v192
	v_exp_f32_e32 v193, v193
	v_exp_f32_e32 v194, v194
	v_exp_f32_e32 v195, v195
	v_exp_f32_e32 v196, v196
	v_exp_f32_e32 v197, v197
	v_mul_f32_e32 v198, v92, v76
	v_mul_f32_e32 v199, v93, v77
	v_mul_f32_e32 v200, v94, v78
	v_mul_f32_e32 v201, v95, v79
	v_mul_f32_e32 v202, v84, v68
	v_mul_f32_e32 v203, v85, v69
	v_mul_f32_e32 v204, v86, v70
	v_mul_f32_e32 v205, v87, v71
	v_fma_f32 v190, v190, v244, v244
	v_fma_f32 v191, v191, v244, v244
	v_fma_f32 v192, v192, v244, v244
	v_fma_f32 v193, v193, v244, v244
	v_fma_f32 v194, v194, v244, v244
	v_fma_f32 v195, v195, v244, v244
	v_fma_f32 v196, v196, v244, v244
	v_fma_f32 v197, v197, v244, v244
	v_rcp_f32_e32 v190, v190
	v_rcp_f32_e32 v191, v191
	v_rcp_f32_e32 v192, v192
	v_rcp_f32_e32 v193, v193
	v_rcp_f32_e32 v194, v194
	v_rcp_f32_e32 v195, v195
	v_rcp_f32_e32 v196, v196
	v_rcp_f32_e32 v197, v197
	s_nop 0
	v_mul_f32_e32 v198, v198, v190
	v_mul_f32_e32 v199, v199, v191
	v_mul_f32_e32 v200, v200, v192
	v_mul_f32_e32 v201, v201, v193
	v_mul_f32_e32 v202, v202, v194
	v_mul_f32_e32 v203, v203, v195
	v_mul_f32_e32 v204, v204, v196
	v_mul_f32_e32 v205, v205, v197
	v_cvt_pk_bf16_f32 v190, v198, v199
	v_cvt_pk_bf16_f32 v191, v200, v201
	v_cvt_pk_bf16_f32 v192, v202, v203
	v_cvt_pk_bf16_f32 v193, v204, v205
	global_store_dwordx4 v[174:175], v[190:193], off
	v_lshl_add_u64 v[174:175], v[174:175], 0, s[78:79]
	v_mul_f32_e32 v206, v253, v88
	v_mul_f32_e32 v207, v253, v89
	v_mul_f32_e32 v208, v253, v90
	v_mul_f32_e32 v209, v253, v91
	v_mul_f32_e32 v210, v253, v80
	v_mul_f32_e32 v211, v253, v81
	v_mul_f32_e32 v212, v253, v82
	v_mul_f32_e32 v213, v253, v83
	v_exp_f32_e32 v206, v206
	v_exp_f32_e32 v207, v207
	v_exp_f32_e32 v208, v208
	v_exp_f32_e32 v209, v209
	v_exp_f32_e32 v210, v210
	v_exp_f32_e32 v211, v211
	v_exp_f32_e32 v212, v212
	v_exp_f32_e32 v213, v213
	v_mul_f32_e32 v214, v88, v72
	v_mul_f32_e32 v215, v89, v73
	v_mul_f32_e32 v216, v90, v74
	v_mul_f32_e32 v217, v91, v75
	v_mul_f32_e32 v218, v80, v64
	v_mul_f32_e32 v219, v81, v65
	v_mul_f32_e32 v220, v82, v66
	v_mul_f32_e32 v221, v83, v67
	v_fma_f32 v206, v206, v245, v245
	v_fma_f32 v207, v207, v245, v245
	v_fma_f32 v208, v208, v245, v245
	v_fma_f32 v209, v209, v245, v245
	v_fma_f32 v210, v210, v245, v245
	v_fma_f32 v211, v211, v245, v245
	v_fma_f32 v212, v212, v245, v245
	v_fma_f32 v213, v213, v245, v245
	v_rcp_f32_e32 v206, v206
	v_rcp_f32_e32 v207, v207
	v_rcp_f32_e32 v208, v208
	v_rcp_f32_e32 v209, v209
	v_rcp_f32_e32 v210, v210
	v_rcp_f32_e32 v211, v211
	v_rcp_f32_e32 v212, v212
	v_rcp_f32_e32 v213, v213
	s_nop 0
	v_mul_f32_e32 v214, v214, v206
	v_mul_f32_e32 v215, v215, v207
	v_mul_f32_e32 v216, v216, v208
	v_mul_f32_e32 v217, v217, v209
	v_mul_f32_e32 v218, v218, v210
	v_mul_f32_e32 v219, v219, v211
	v_mul_f32_e32 v220, v220, v212
	v_mul_f32_e32 v221, v221, v213
	v_cvt_pk_bf16_f32 v206, v214, v215
	v_cvt_pk_bf16_f32 v207, v216, v217
	v_cvt_pk_bf16_f32 v208, v218, v219
	v_cvt_pk_bf16_f32 v209, v220, v221
	global_store_dwordx4 v[174:175], v[206:209], off
	v_mul_f32_e32 v190, v168, v60
	v_mul_f32_e32 v191, v168, v61
	v_mul_f32_e32 v192, v168, v62
	v_mul_f32_e32 v193, v168, v63
	v_mul_f32_e32 v194, v168, v56
	v_mul_f32_e32 v195, v168, v57
	v_mul_f32_e32 v196, v168, v58
	v_mul_f32_e32 v197, v168, v59
	v_exp_f32_e32 v190, v190
	v_exp_f32_e32 v191, v191
	v_exp_f32_e32 v192, v192
	v_exp_f32_e32 v193, v193
	v_exp_f32_e32 v194, v194
	v_exp_f32_e32 v195, v195
	v_exp_f32_e32 v196, v196
	v_exp_f32_e32 v197, v197
	v_mul_f32_e32 v198, v60, v44
	v_mul_f32_e32 v199, v61, v45
	v_mul_f32_e32 v200, v62, v46
	v_mul_f32_e32 v201, v63, v47
	v_mul_f32_e32 v202, v56, v36
	v_mul_f32_e32 v203, v57, v37
	v_mul_f32_e32 v204, v58, v38
	v_mul_f32_e32 v205, v59, v39
	v_fma_f32 v190, v190, v246, v246
	v_fma_f32 v191, v191, v246, v246
	v_fma_f32 v192, v192, v246, v246
	v_fma_f32 v193, v193, v246, v246
	v_fma_f32 v194, v194, v246, v246
	v_fma_f32 v195, v195, v246, v246
	v_fma_f32 v196, v196, v246, v246
	v_fma_f32 v197, v197, v246, v246
	v_rcp_f32_e32 v190, v190
	v_rcp_f32_e32 v191, v191
	v_rcp_f32_e32 v192, v192
	v_rcp_f32_e32 v193, v193
	v_rcp_f32_e32 v194, v194
	v_rcp_f32_e32 v195, v195
	v_rcp_f32_e32 v196, v196
	v_rcp_f32_e32 v197, v197
	s_nop 0
	v_mul_f32_e32 v198, v198, v190
	v_mul_f32_e32 v199, v199, v191
	v_mul_f32_e32 v200, v200, v192
	v_mul_f32_e32 v201, v201, v193
	v_mul_f32_e32 v202, v202, v194
	v_mul_f32_e32 v203, v203, v195
	v_mul_f32_e32 v204, v204, v196
	v_mul_f32_e32 v205, v205, v197
	v_cvt_pk_bf16_f32 v190, v198, v199
	v_cvt_pk_bf16_f32 v191, v200, v201
	v_cvt_pk_bf16_f32 v192, v202, v203
	v_cvt_pk_bf16_f32 v193, v204, v205
	global_store_dwordx4 v[166:167], v[190:193], off
	v_lshl_add_u64 v[166:167], v[166:167], 0, s[78:79]
	v_mul_f32_e32 v206, v170, v52
	v_mul_f32_e32 v207, v170, v53
	v_mul_f32_e32 v208, v170, v54
	v_mul_f32_e32 v209, v170, v55
	v_mul_f32_e32 v210, v170, v48
	v_mul_f32_e32 v211, v170, v49
	v_mul_f32_e32 v212, v170, v50
	v_mul_f32_e32 v213, v170, v51
	v_exp_f32_e32 v206, v206
	v_exp_f32_e32 v207, v207
	v_exp_f32_e32 v208, v208
	v_exp_f32_e32 v209, v209
	v_exp_f32_e32 v210, v210
	v_exp_f32_e32 v211, v211
	v_exp_f32_e32 v212, v212
	v_exp_f32_e32 v213, v213
	v_mul_f32_e32 v214, v52, v40
	v_mul_f32_e32 v215, v53, v41
	v_mul_f32_e32 v216, v54, v42
	v_mul_f32_e32 v217, v55, v43
	v_mul_f32_e32 v218, v48, v32
	v_mul_f32_e32 v219, v49, v33
	v_mul_f32_e32 v220, v50, v34
	v_mul_f32_e32 v221, v51, v35
	v_fma_f32 v206, v206, v247, v247
	v_fma_f32 v207, v207, v247, v247
	v_fma_f32 v208, v208, v247, v247
	v_fma_f32 v209, v209, v247, v247
	v_fma_f32 v210, v210, v247, v247
	v_fma_f32 v211, v211, v247, v247
	v_fma_f32 v212, v212, v247, v247
	v_fma_f32 v213, v213, v247, v247
	v_rcp_f32_e32 v206, v206
	v_rcp_f32_e32 v207, v207
	v_rcp_f32_e32 v208, v208
	v_rcp_f32_e32 v209, v209
	v_rcp_f32_e32 v210, v210
	v_rcp_f32_e32 v211, v211
	v_rcp_f32_e32 v212, v212
	v_rcp_f32_e32 v213, v213
	s_nop 0
	v_mul_f32_e32 v214, v214, v206
	v_mul_f32_e32 v215, v215, v207
	v_mul_f32_e32 v216, v216, v208
	v_mul_f32_e32 v217, v217, v209
	v_mul_f32_e32 v218, v218, v210
	v_mul_f32_e32 v219, v219, v211
	v_mul_f32_e32 v220, v220, v212
	v_mul_f32_e32 v221, v221, v213
	v_cvt_pk_bf16_f32 v206, v214, v215
	v_cvt_pk_bf16_f32 v207, v216, v217
	v_cvt_pk_bf16_f32 v208, v218, v219
	v_cvt_pk_bf16_f32 v209, v220, v221
	global_store_dwordx4 v[166:167], v[206:209], off
	v_lshl_add_u64 v[166:167], v[166:167], 0, s[78:79]
	v_mul_f32_e32 v190, v176, v28
	v_mul_f32_e32 v191, v176, v29
	v_mul_f32_e32 v192, v176, v30
	v_mul_f32_e32 v193, v176, v31
	v_mul_f32_e32 v194, v176, v20
	v_mul_f32_e32 v195, v176, v21
	v_mul_f32_e32 v196, v176, v22
	v_mul_f32_e32 v197, v176, v23
	v_exp_f32_e32 v190, v190
	v_exp_f32_e32 v191, v191
	v_exp_f32_e32 v192, v192
	v_exp_f32_e32 v193, v193
	v_exp_f32_e32 v194, v194
	v_exp_f32_e32 v195, v195
	v_exp_f32_e32 v196, v196
	v_exp_f32_e32 v197, v197
	v_mul_f32_e32 v198, v28, v12
	v_mul_f32_e32 v199, v29, v13
	v_mul_f32_e32 v200, v30, v14
	v_mul_f32_e32 v201, v31, v15
	v_mul_f32_e32 v202, v20, v4
	v_mul_f32_e32 v203, v21, v5
	v_mul_f32_e32 v204, v22, v6
	v_mul_f32_e32 v205, v23, v7
	v_fma_f32 v190, v190, v248, v248
	v_fma_f32 v191, v191, v248, v248
	v_fma_f32 v192, v192, v248, v248
	v_fma_f32 v193, v193, v248, v248
	v_fma_f32 v194, v194, v248, v248
	v_fma_f32 v195, v195, v248, v248
	v_fma_f32 v196, v196, v248, v248
	v_fma_f32 v197, v197, v248, v248
	v_rcp_f32_e32 v190, v190
	v_rcp_f32_e32 v191, v191
	v_rcp_f32_e32 v192, v192
	v_rcp_f32_e32 v193, v193
	v_rcp_f32_e32 v194, v194
	v_rcp_f32_e32 v195, v195
	v_rcp_f32_e32 v196, v196
	v_rcp_f32_e32 v197, v197
	s_nop 0
	v_mul_f32_e32 v198, v198, v190
	v_mul_f32_e32 v199, v199, v191
	v_mul_f32_e32 v200, v200, v192
	v_mul_f32_e32 v201, v201, v193
	v_mul_f32_e32 v202, v202, v194
	v_mul_f32_e32 v203, v203, v195
	v_mul_f32_e32 v204, v204, v196
	v_mul_f32_e32 v205, v205, v197
	v_cvt_pk_bf16_f32 v190, v198, v199
	v_cvt_pk_bf16_f32 v191, v200, v201
	v_cvt_pk_bf16_f32 v192, v202, v203
	v_cvt_pk_bf16_f32 v193, v204, v205
	global_store_dwordx4 v[166:167], v[190:193], off
	v_lshl_add_u64 v[166:167], v[166:167], 0, s[78:79]
	v_mul_f32_e32 v206, v178, v24
	v_mul_f32_e32 v207, v178, v25
	v_mul_f32_e32 v208, v178, v26
	v_mul_f32_e32 v209, v178, v27
	v_mul_f32_e32 v210, v178, v16
	v_mul_f32_e32 v211, v178, v17
	v_mul_f32_e32 v212, v178, v18
	v_mul_f32_e32 v213, v178, v19
	v_exp_f32_e32 v206, v206
	v_exp_f32_e32 v207, v207
	v_exp_f32_e32 v208, v208
	v_exp_f32_e32 v209, v209
	v_exp_f32_e32 v210, v210
	v_exp_f32_e32 v211, v211
	v_exp_f32_e32 v212, v212
	v_exp_f32_e32 v213, v213
	v_mul_f32_e32 v214, v24, v8
	v_mul_f32_e32 v215, v25, v9
	v_mul_f32_e32 v216, v26, v10
	v_mul_f32_e32 v217, v27, v11
	v_mul_f32_e32 v218, v16, v0
	v_mul_f32_e32 v219, v17, v1
	v_mul_f32_e32 v220, v18, v2
	v_mul_f32_e32 v221, v19, v3
	v_fma_f32 v206, v206, v249, v249
	v_fma_f32 v207, v207, v249, v249
	v_fma_f32 v208, v208, v249, v249
	v_fma_f32 v209, v209, v249, v249
	v_fma_f32 v210, v210, v249, v249
	v_fma_f32 v211, v211, v249, v249
	v_fma_f32 v212, v212, v249, v249
	v_fma_f32 v213, v213, v249, v249
	v_rcp_f32_e32 v206, v206
	v_rcp_f32_e32 v207, v207
	v_rcp_f32_e32 v208, v208
	v_rcp_f32_e32 v209, v209
	v_rcp_f32_e32 v210, v210
	v_rcp_f32_e32 v211, v211
	v_rcp_f32_e32 v212, v212
	v_rcp_f32_e32 v213, v213
	s_nop 0
	v_mul_f32_e32 v214, v214, v206
	v_mul_f32_e32 v215, v215, v207
	v_mul_f32_e32 v216, v216, v208
	v_mul_f32_e32 v217, v217, v209
	v_mul_f32_e32 v218, v218, v210
	v_mul_f32_e32 v219, v219, v211
	v_mul_f32_e32 v220, v220, v212
	v_mul_f32_e32 v221, v221, v213
	v_cvt_pk_bf16_f32 v206, v214, v215
	v_cvt_pk_bf16_f32 v207, v216, v217
	v_cvt_pk_bf16_f32 v208, v218, v219
	v_cvt_pk_bf16_f32 v209, v220, v221
	global_store_dwordx4 v[166:167], v[206:209], off
	s_branch .LBB0_514

.LBB0_549:
	v_mov_b32_e32 v242, 0x8000
	v_mov_b32_e32 v243, 0x358637bd
	v_mov_b32_e32 v244, 0xfffe8000
	v_mov_b32_e32 v245, 0xffff4000
	v_mov_b32_e32 v246, 0xfffff500
	v_mov_b32_e32 v247, 0x41b17218
	v_mov_b32_e32 v168, 0x3a27c5ac
	v_mov_b32_e32 v170, 0x260
	v_mov_b32_e32 v176, 12
	v_mov_b32_e32 v178, 0xffffea00
	s_waitcnt vmcnt(0)
	v_readlane_b32 s76, v255, 10
	s_cmpk_gt_u32 s87, 0xff
	s_mov_b64 s[72:73], s[0:1]
	v_readlane_b32 s77, v255, 11
	s_mov_b32 s64, 0x2aaaaaab
	s_movk_i32 s94, 0x300
	s_movk_i32 s97, 0xea00
	s_movk_i32 s68, 0x200
	s_movk_i32 s83, 0x81
	s_cbranch_scc1 .LBB0_486
	s_barrier
	s_branch .LBB0_486

	.amdhsa_kernel _Z10fwd_kernel6Params
		.amdhsa_group_segment_fixed_size 0
		.amdhsa_private_segment_fixed_size 0
		.amdhsa_kernarg_size 544
		.amdhsa_user_sgpr_count 2
		.amdhsa_user_sgpr_dispatch_ptr 0
		.amdhsa_user_sgpr_queue_ptr 0
		.amdhsa_user_sgpr_kernarg_segment_ptr 1
		.amdhsa_user_sgpr_dispatch_id 0
		.amdhsa_user_sgpr_kernarg_preload_length 0
		.amdhsa_user_sgpr_kernarg_preload_offset 0
		.amdhsa_user_sgpr_private_segment_size 0
		.amdhsa_uses_dynamic_stack 0
		.amdhsa_enable_private_segment 0
		.amdhsa_system_sgpr_workgroup_id_x 1
		.amdhsa_system_sgpr_workgroup_id_y 0
		.amdhsa_system_sgpr_workgroup_id_z 0
		.amdhsa_system_sgpr_workgroup_info 0
		.amdhsa_system_vgpr_workitem_id 2
		.amdhsa_next_free_vgpr 256
		.amdhsa_next_free_sgpr 102
		.amdhsa_accum_offset 256
		.amdhsa_reserve_vcc 1
		.amdhsa_float_round_mode_32 0
		.amdhsa_float_round_mode_16_64 0
		.amdhsa_float_denorm_mode_32 3
		.amdhsa_float_denorm_mode_16_64 3
		.amdhsa_dx10_clamp 1
		.amdhsa_ieee_mode 1
		.amdhsa_fp16_overflow 0
		.amdhsa_tg_split 0
		.amdhsa_exception_fp_ieee_invalid_op 0
		.amdhsa_exception_fp_denorm_src 0
		.amdhsa_exception_fp_ieee_div_zero 0
		.amdhsa_exception_fp_ieee_overflow 0
		.amdhsa_exception_fp_ieee_underflow 0
		.amdhsa_exception_fp_ieee_inexact 0
		.amdhsa_exception_int_div_zero 0
	.end_amdhsa_kernel

amdhsa.kernels:
  - .agpr_count:     0
    .args:
      - .offset:         0
        .size:           288
        .value_kind:     by_value
      - .offset:         288
        .size:           4
        .value_kind:     hidden_block_count_x
      - .offset:         292
        .size:           4
        .value_kind:     hidden_block_count_y
      - .offset:         296
        .size:           4
        .value_kind:     hidden_block_count_z
      - .offset:         300
        .size:           2
        .value_kind:     hidden_group_size_x
      - .offset:         302
        .size:           2
        .value_kind:     hidden_group_size_y
      - .offset:         304
        .size:           2
        .value_kind:     hidden_group_size_z
      - .offset:         306
        .size:           2
        .value_kind:     hidden_remainder_x
      - .offset:         308
        .size:           2
        .value_kind:     hidden_remainder_y
      - .offset:         310
        .size:           2
        .value_kind:     hidden_remainder_z
      - .offset:         328
        .size:           8
        .value_kind:     hidden_global_offset_x
      - .offset:         336
        .size:           8
        .value_kind:     hidden_global_offset_y
      - .offset:         344
        .size:           8
        .value_kind:     hidden_global_offset_z
      - .offset:         352
        .size:           2
        .value_kind:     hidden_grid_dims
      - .offset:         376
        .size:           8
        .value_kind:     hidden_multigrid_sync_arg
      - .offset:         408
        .size:           4
        .value_kind:     hidden_dynamic_lds_size
    .group_segment_fixed_size: 0
    .kernarg_segment_align: 8
    .kernarg_segment_size: 544
    .language:       OpenCL C
    .language_version:
      - 2
      - 0
    .max_flat_workgroup_size: 512
    .name:           _Z10fwd_kernel6Params
    .private_segment_fixed_size: 0
    .sgpr_count:     108
    .sgpr_spill_count: 83
    .symbol:         _Z10fwd_kernel6Params.kd
    .uniform_work_group_size: 1
    .uses_dynamic_stack: false
    .vgpr_count:     256
    .vgpr_spill_count: 0
    .wavefront_size: 64
